# v18sc1
# baseline (speedup 1.0000x reference)
; __device__ __forceinline__ int otid() { int t = threadIdx.x; asm volatile("" : "+v"(t)); return t; }
; #define PG8_BAR __builtin_amdgcn_s_barrier()
; __device__ __forceinline__ u32x4 pack8(f32x4 v0, f32x4 v1) { u32x4 w; w.x = cvt_pk_bf16(v0[0], v0[1]); w.y = cvt_pk_bf16(v0[2], v0[3]); w.z = cvt_pk_bf16(v1[0], v1[1]); w.w = cvt_pk_bf16(v1[2], v1[3]); return w; }
;     ...
;         if (wr == 0) PG8_BAR;
;         { const int t2_ = otid(), w2_ = t2_ >> 6, l2_ = t2_ & 63; E(acc, cur, w2_ >> 2, w2_ & 3, l2_ & 15, l2_ >> 4); }
;         if (!has_next) break;
; #pragma unroll
;         for (int a = 0; a < 2; ++a)
; #pragma unroll
;             for (int b = 0; b < 2; ++b)
; #pragma unroll
;                 for (int m = 0; m < 4; ++m)
; #pragma unroll
;                     for (int n = 0; n < 2; ++n) acc[a][b][m][n] = (f32x4){0.f, 0.f, 0.f, 0.f};
;         cur = nxt; cA = nA; cB = nB; ++ui;
;         if (wr == 1) PG8_BAR;
;     __device__ __forceinline__ void operator()(const f32x4 (&acc)[2][2][4][2], const Unit& u, int wr, int wc, int fr, int fq) const {
;         bf16_t* O_ = O + col0;
; #pragma unroll
;         for (int ai = 0; ai < 2; ++ai)
; #pragma unroll
;             for (int m = 0; m < 4; ++m) { const int row = u.pm * BM + ai * HALF + wr * 64 + m * 16 + fr;
; #pragma unroll
;                 for (int bj = 0; bj < 2; ++bj) { const int col = u.pn * BM + bj * HALF + wc * 32 + 8 * fq;
;                     *(u32x4*)(O_ + (size_t)row * NP + col) = pack8(acc[ai][bj][m][0], acc[ai][bj][m][1]); } }
;     }
.LBB0_665:
	v_mov_b32_e32 v134, v199
	v_cvt_pk_bf16_f32 v126, v126, v127
	v_cvt_pk_bf16_f32 v127, v128, v129
	v_cvt_pk_bf16_f32 v128, v122, v123
	v_cvt_pk_bf16_f32 v129, v124, v125
	v_readlane_b32 s74, v253, 24
	v_ashrrev_i32_e32 v135, 2, v134
	v_and_b32_e32 v135, 0xffffffc0, v135
	v_lshl_add_u32 v135, s68, 8, v135
	v_and_or_b32 v142, v134, 15, v135
	v_lshrrev_b32_e32 v134, 1, v134
	v_and_b32_e32 v134, 0x78, v134
	v_lshl_or_b32 v138, s93, 8, v134
	v_mov_b64_e32 v[134:135], s[44:45]
	v_ashrrev_i32_e32 v139, 31, v138
	v_mad_i64_i32 v[140:141], s[34:35], v142, s31, v[134:135]
	v_lshlrev_b64 v[122:123], 1, v[138:139]
	v_lshl_add_u64 v[124:125], v[140:141], 0, v[122:123]
	flat_store_dwordx4 v[124:125], v[126:129] sc1
	v_cvt_pk_bf16_f32 v114, v114, v115
	v_cvt_pk_bf16_f32 v115, v116, v117
	v_cvt_pk_bf16_f32 v116, v106, v107
	v_or_b32_e32 v106, 16, v142
	v_cvt_pk_bf16_f32 v117, v108, v109
	flat_store_dwordx4 v[124:125], v[114:117] offset:256 sc1
	s_andn2_b64 vcc, exec, s[40:41]
	s_mov_b64 s[40:41], -1
	v_mad_i64_i32 v[114:115], s[34:35], v106, s31, v[134:135]
	v_cvt_pk_bf16_f32 v106, v118, v119
	v_cvt_pk_bf16_f32 v107, v120, v121
	v_cvt_pk_bf16_f32 v108, v110, v111
	v_lshl_add_u64 v[110:111], v[114:115], 0, v[122:123]
	v_cvt_pk_bf16_f32 v109, v112, v113
	flat_store_dwordx4 v[110:111], v[106:109] sc1
	v_cvt_pk_bf16_f32 v98, v98, v99
	v_cvt_pk_bf16_f32 v99, v100, v101
	v_cvt_pk_bf16_f32 v100, v90, v91
	v_or_b32_e32 v90, 32, v142
	v_cvt_pk_bf16_f32 v101, v92, v93
	flat_store_dwordx4 v[110:111], v[98:101] offset:256 sc1
	v_readlane_b32 s75, v253, 25
	s_nop 0
	v_mad_i64_i32 v[98:99], s[34:35], v90, s31, v[134:135]
	v_cvt_pk_bf16_f32 v90, v102, v103
	v_cvt_pk_bf16_f32 v91, v104, v105
	v_cvt_pk_bf16_f32 v92, v94, v95
	v_lshl_add_u64 v[94:95], v[98:99], 0, v[122:123]
	v_cvt_pk_bf16_f32 v93, v96, v97
	flat_store_dwordx4 v[94:95], v[90:93] sc1
	v_cvt_pk_bf16_f32 v82, v82, v83
	v_cvt_pk_bf16_f32 v83, v84, v85
	v_cvt_pk_bf16_f32 v84, v74, v75
	v_or_b32_e32 v74, 48, v142
	v_cvt_pk_bf16_f32 v85, v76, v77
	flat_store_dwordx4 v[94:95], v[82:85] offset:256 sc1
	s_nop 1
	v_mad_i64_i32 v[82:83], s[34:35], v74, s31, v[134:135]
	v_cvt_pk_bf16_f32 v74, v86, v87
	v_cvt_pk_bf16_f32 v75, v88, v89
	v_cvt_pk_bf16_f32 v76, v78, v79
	v_lshl_add_u64 v[78:79], v[82:83], 0, v[122:123]
	v_cvt_pk_bf16_f32 v77, v80, v81
	flat_store_dwordx4 v[78:79], v[74:77] sc1
	v_cvt_pk_bf16_f32 v70, v70, v71
	v_cvt_pk_bf16_f32 v71, v72, v73
	v_cvt_pk_bf16_f32 v72, v66, v67
	v_add_u32_e32 v66, 0x80, v142
	v_mad_i64_i32 v[66:67], s[34:35], v66, s31, v[134:135]
	v_cvt_pk_bf16_f32 v73, v68, v69
	flat_store_dwordx4 v[78:79], v[70:73] offset:256 sc1
	v_cvt_pk_bf16_f32 v62, v62, v63
	v_cvt_pk_bf16_f32 v63, v64, v65
	v_cvt_pk_bf16_f32 v64, v58, v59
	v_lshl_add_u64 v[58:59], v[66:67], 0, v[122:123]
	v_cvt_pk_bf16_f32 v65, v60, v61
	flat_store_dwordx4 v[58:59], v[62:65] sc1
	v_cvt_pk_bf16_f32 v50, v50, v51
	v_cvt_pk_bf16_f32 v51, v52, v53
	v_cvt_pk_bf16_f32 v52, v42, v43
	v_add_u32_e32 v42, 0x90, v142
	v_cvt_pk_bf16_f32 v53, v44, v45
	flat_store_dwordx4 v[58:59], v[50:53] offset:256 sc1
	s_nop 1
	v_mad_i64_i32 v[50:51], s[34:35], v42, s31, v[134:135]
	v_cvt_pk_bf16_f32 v42, v54, v55
	v_cvt_pk_bf16_f32 v43, v56, v57
	v_cvt_pk_bf16_f32 v44, v46, v47
	v_lshl_add_u64 v[46:47], v[50:51], 0, v[122:123]
	v_cvt_pk_bf16_f32 v45, v48, v49
	flat_store_dwordx4 v[46:47], v[42:45] sc1
	v_cvt_pk_bf16_f32 v34, v34, v35
	v_cvt_pk_bf16_f32 v35, v36, v37
	v_cvt_pk_bf16_f32 v36, v26, v27
	v_add_u32_e32 v26, 0xa0, v142
	v_cvt_pk_bf16_f32 v37, v28, v29
	flat_store_dwordx4 v[46:47], v[34:37] offset:256 sc1
	s_nop 1
	v_mad_i64_i32 v[34:35], s[34:35], v26, s31, v[134:135]
	v_cvt_pk_bf16_f32 v26, v38, v39
	v_cvt_pk_bf16_f32 v27, v40, v41
	v_cvt_pk_bf16_f32 v28, v30, v31
	v_lshl_add_u64 v[30:31], v[34:35], 0, v[122:123]
	v_cvt_pk_bf16_f32 v29, v32, v33
	flat_store_dwordx4 v[30:31], v[26:29] sc1
	v_cvt_pk_bf16_f32 v18, v18, v19
	v_cvt_pk_bf16_f32 v19, v20, v21
	v_cvt_pk_bf16_f32 v20, v10, v11
	v_add_u32_e32 v10, 0xb0, v142
	v_cvt_pk_bf16_f32 v21, v12, v13
	flat_store_dwordx4 v[30:31], v[18:21] offset:256 sc1
	s_nop 1
	v_mad_i64_i32 v[18:19], s[34:35], v10, s31, v[134:135]
	v_cvt_pk_bf16_f32 v10, v22, v23
	v_cvt_pk_bf16_f32 v11, v24, v25
	v_cvt_pk_bf16_f32 v12, v14, v15
	v_lshl_add_u64 v[14:15], v[18:19], 0, v[122:123]
	v_readlane_b32 s34, v253, 11
	v_cvt_pk_bf16_f32 v13, v16, v17
	flat_store_dwordx4 v[14:15], v[10:13] sc1
	v_cvt_pk_bf16_f32 v6, v6, v7
	v_cvt_pk_bf16_f32 v7, v8, v9
	v_cvt_pk_bf16_f32 v8, v2, v3
	v_cvt_pk_bf16_f32 v9, v4, v5
	flat_store_dwordx4 v[14:15], v[6:9] offset:256 sc1
	v_readlane_b32 s35, v253, 12
	s_load_dwordx2 s[96:97], s[34:35], 0x98
	s_cbranch_vccnz .LBB0_658
	v_readlane_b32 s12, v253, 38
	v_readlane_b32 s13, v253, 39
	s_andn2_b64 vcc, exec, s[12:13]
	s_cbranch_vccnz .LBB0_657
	s_barrier
	s_branch .LBB0_657
